# K-loop LDS-DMA loads with sc1 (L1 bypass) in all three GEMM loops
# baseline (speedup 1.0000x reference)
.LBB0_180:
	ds_read_b128 v[152:155], v159
	ds_read_b128 v[162:165], v159 offset:1024
	ds_read_b128 v[166:169], v159 offset:2048
	ds_read_b128 v[170:173], v159 offset:3072
	ds_read_b128 v[174:177], v160
	ds_read_b128 v[178:181], v160 offset:1024
	ds_read_b128 v[182:185], v160 offset:2048
	ds_read_b128 v[186:189], v160 offset:3072
	s_add_u32 s4, s0, 0xfffc0080
	s_addc_u32 s5, s1, -1
	s_cmp_eq_u32 vcc_lo, 12
	s_cselect_b32 s83, s39, s5
	s_cselect_b32 s82, s38, s4
	s_cselect_b32 s5, s73, s79
	s_cselect_b32 s4, s72, s53
	v_lshl_add_u64 v[198:199], s[0:1], 0, v[144:145]
	s_add_i32 m0, s43, 0xc000
	ds_read_b128 v[190:193], v161
	ds_read_b128 v[194:197], v161 offset:1024
	ds_read_b128 v[202:205], v161 offset:2048
	ds_read_b128 v[206:209], v161 offset:3072
	ds_read_b128 v[210:213], v161 offset:4096
	ds_read_b128 v[214:217], v161 offset:5120
	ds_read_b128 v[218:221], v161 offset:6144
	ds_read_b128 v[222:225], v161 offset:7168
	global_load_lds_dwordx4 v[198:199], off sc1
	v_lshl_add_u64 v[198:199], s[0:1], 0, v[146:147]
	s_add_i32 m0, s43, 0xe000
	s_nop 0
	global_load_lds_dwordx4 v[198:199], off sc1
	s_waitcnt vmcnt(8)
	s_waitcnt lgkmcnt(0)
	s_barrier
	s_setprio 1
	s_waitcnt lgkmcnt(0)
	v_mfma_f32_16x16x32_bf16 v[124:127], v[152:155], v[190:193], v[124:127]
	v_mfma_f32_16x16x32_bf16 v[120:123], v[166:169], v[190:193], v[120:123]
	v_mfma_f32_16x16x32_bf16 v[108:111], v[152:155], v[202:205], v[108:111]
	v_mfma_f32_16x16x32_bf16 v[104:107], v[166:169], v[202:205], v[104:107]
	v_mfma_f32_16x16x32_bf16 v[92:95], v[152:155], v[210:213], v[92:95]
	v_mfma_f32_16x16x32_bf16 v[88:91], v[166:169], v[210:213], v[88:91]
	v_mfma_f32_16x16x32_bf16 v[76:79], v[152:155], v[218:221], v[76:79]
	v_mfma_f32_16x16x32_bf16 v[72:75], v[166:169], v[218:221], v[72:75]
	v_mfma_f32_16x16x32_bf16 v[124:127], v[162:165], v[194:197], v[124:127]
	v_mfma_f32_16x16x32_bf16 v[120:123], v[170:173], v[194:197], v[120:123]
	v_mfma_f32_16x16x32_bf16 v[108:111], v[162:165], v[206:209], v[108:111]
	v_mfma_f32_16x16x32_bf16 v[104:107], v[170:173], v[206:209], v[104:107]
	v_mfma_f32_16x16x32_bf16 v[92:95], v[162:165], v[214:217], v[92:95]
	v_mfma_f32_16x16x32_bf16 v[88:91], v[170:173], v[214:217], v[88:91]
	v_mfma_f32_16x16x32_bf16 v[76:79], v[162:165], v[222:225], v[76:79]
	v_mfma_f32_16x16x32_bf16 v[72:75], v[170:173], v[222:225], v[72:75]
	s_setprio 0
	s_setprio 1
	v_mfma_f32_16x16x32_bf16 v[116:119], v[174:177], v[190:193], v[116:119]
	v_mfma_f32_16x16x32_bf16 v[112:115], v[182:185], v[190:193], v[112:115]
	v_mfma_f32_16x16x32_bf16 v[100:103], v[174:177], v[202:205], v[100:103]
	v_mfma_f32_16x16x32_bf16 v[96:99], v[182:185], v[202:205], v[96:99]
	v_mfma_f32_16x16x32_bf16 v[84:87], v[174:177], v[210:213], v[84:87]
	v_mfma_f32_16x16x32_bf16 v[80:83], v[182:185], v[210:213], v[80:83]
	v_mfma_f32_16x16x32_bf16 v[68:71], v[174:177], v[218:221], v[68:71]
	v_mfma_f32_16x16x32_bf16 v[64:67], v[182:185], v[218:221], v[64:67]
	v_mfma_f32_16x16x32_bf16 v[116:119], v[178:181], v[194:197], v[116:119]
	v_mfma_f32_16x16x32_bf16 v[112:115], v[186:189], v[194:197], v[112:115]
	v_mfma_f32_16x16x32_bf16 v[100:103], v[178:181], v[206:209], v[100:103]
	v_mfma_f32_16x16x32_bf16 v[96:99], v[186:189], v[206:209], v[96:99]
	v_mfma_f32_16x16x32_bf16 v[84:87], v[178:181], v[214:217], v[84:87]
	v_mfma_f32_16x16x32_bf16 v[80:83], v[186:189], v[214:217], v[80:83]
	v_mfma_f32_16x16x32_bf16 v[68:71], v[178:181], v[222:225], v[68:71]
	v_mfma_f32_16x16x32_bf16 v[64:67], v[186:189], v[222:225], v[64:67]
	s_setprio 0
	s_barrier
	s_add_i32 s12, s9, s3
	v_lshl_add_u64 v[198:199], s[4:5], 0, v[132:133]
	s_mov_b32 m0, s12
	ds_read_b128 v[190:193], v161 offset:16384
	ds_read_b128 v[194:197], v161 offset:17408
	ds_read_b128 v[202:205], v161 offset:18432
	ds_read_b128 v[206:209], v161 offset:19456
	ds_read_b128 v[210:213], v161 offset:20480
	ds_read_b128 v[214:217], v161 offset:21504
	ds_read_b128 v[218:221], v161 offset:22528
	ds_read_b128 v[222:225], v161 offset:23552
	global_load_lds_dwordx4 v[198:199], off sc1
	s_add_i32 m0, s12, 0x2000
	s_add_u32 s12, s4, 0x40000
	v_lshl_add_u64 v[226:227], s[4:5], 0, v[128:129]
	s_addc_u32 s13, s5, 0
	s_add_i32 vcc_hi, s10, s3
	global_load_lds_dwordx4 v[226:227], off sc1
	v_lshl_add_u64 v[228:229], s[12:13], 0, v[132:133]
	s_mov_b32 m0, vcc_hi
	v_lshl_add_u64 v[230:231], s[82:83], 0, v[130:131]
	global_load_lds_dwordx4 v[228:229], off sc1
	v_lshl_add_u64 v[228:229], s[12:13], 0, v[128:129]
	s_add_i32 m0, vcc_hi, 0x2000
	s_nop 0
	global_load_lds_dwordx4 v[228:229], off sc1
	v_lshl_add_u64 v[228:229], s[82:83], 0, v[134:135]
	s_mov_b32 m0, s43
	s_nop 0
	global_load_lds_dwordx4 v[228:229], off sc1
	s_mov_b32 m0, s75
	s_nop 0
	global_load_lds_dwordx4 v[230:231], off sc1
	s_waitcnt vmcnt(8)
	s_waitcnt lgkmcnt(0)
	s_barrier
	s_setprio 1
	s_waitcnt lgkmcnt(0)
	v_mfma_f32_16x16x32_bf16 v[60:63], v[152:155], v[190:193], v[60:63]
	v_mfma_f32_16x16x32_bf16 v[56:59], v[166:169], v[190:193], v[56:59]
	v_mfma_f32_16x16x32_bf16 v[44:47], v[152:155], v[202:205], v[44:47]
	v_mfma_f32_16x16x32_bf16 v[40:43], v[166:169], v[202:205], v[40:43]
	v_mfma_f32_16x16x32_bf16 v[28:31], v[152:155], v[210:213], v[28:31]
	v_mfma_f32_16x16x32_bf16 v[24:27], v[166:169], v[210:213], v[24:27]
	v_mfma_f32_16x16x32_bf16 v[12:15], v[152:155], v[218:221], v[12:15]
	v_mfma_f32_16x16x32_bf16 v[8:11], v[166:169], v[218:221], v[8:11]
	v_mfma_f32_16x16x32_bf16 v[60:63], v[162:165], v[194:197], v[60:63]
	v_mfma_f32_16x16x32_bf16 v[56:59], v[170:173], v[194:197], v[56:59]
	v_mfma_f32_16x16x32_bf16 v[44:47], v[162:165], v[206:209], v[44:47]
	v_mfma_f32_16x16x32_bf16 v[40:43], v[170:173], v[206:209], v[40:43]
	v_mfma_f32_16x16x32_bf16 v[28:31], v[162:165], v[214:217], v[28:31]
	v_mfma_f32_16x16x32_bf16 v[24:27], v[170:173], v[214:217], v[24:27]
	v_mfma_f32_16x16x32_bf16 v[12:15], v[162:165], v[222:225], v[12:15]
	v_mfma_f32_16x16x32_bf16 v[8:11], v[170:173], v[222:225], v[8:11]
	s_setprio 0
	s_setprio 1
	v_mfma_f32_16x16x32_bf16 v[52:55], v[174:177], v[190:193], v[52:55]
	v_mfma_f32_16x16x32_bf16 v[48:51], v[182:185], v[190:193], v[48:51]
	v_mfma_f32_16x16x32_bf16 v[36:39], v[174:177], v[202:205], v[36:39]
	v_mfma_f32_16x16x32_bf16 v[32:35], v[182:185], v[202:205], v[32:35]
	v_mfma_f32_16x16x32_bf16 v[20:23], v[174:177], v[210:213], v[20:23]
	v_mfma_f32_16x16x32_bf16 v[16:19], v[182:185], v[210:213], v[16:19]
	v_mfma_f32_16x16x32_bf16 v[4:7], v[174:177], v[218:221], v[4:7]
	v_mfma_f32_16x16x32_bf16 v[0:3], v[182:185], v[218:221], v[0:3]
	v_mfma_f32_16x16x32_bf16 v[52:55], v[178:181], v[194:197], v[52:55]
	v_mfma_f32_16x16x32_bf16 v[48:51], v[186:189], v[194:197], v[48:51]
	v_mfma_f32_16x16x32_bf16 v[36:39], v[178:181], v[206:209], v[36:39]
	v_mfma_f32_16x16x32_bf16 v[32:35], v[186:189], v[206:209], v[32:35]
	v_mfma_f32_16x16x32_bf16 v[20:23], v[178:181], v[214:217], v[20:23]
	v_mfma_f32_16x16x32_bf16 v[16:19], v[186:189], v[214:217], v[16:19]
	v_mfma_f32_16x16x32_bf16 v[4:7], v[178:181], v[222:225], v[4:7]
	v_mfma_f32_16x16x32_bf16 v[0:3], v[186:189], v[222:225], v[0:3]
	s_setprio 0
	s_barrier
	s_add_i32 vcc_hi, 0, 0x18000
	v_add_u32_e32 v136, vcc_hi, v156
	s_add_i32 s14, 0, 0x1c000
	ds_read_b128 v[152:155], v136
	ds_read_b128 v[162:165], v136 offset:1024
	ds_read_b128 v[166:169], v136 offset:2048
	ds_read_b128 v[170:173], v136 offset:3072
	v_add_u32_e32 v136, s14, v156
	ds_read_b128 v[174:177], v136
	ds_read_b128 v[178:181], v136 offset:1024
	ds_read_b128 v[182:185], v136 offset:2048
	ds_read_b128 v[186:189], v136 offset:3072
	s_add_u32 s12, s82, 0x40000
	s_addc_u32 s13, s83, 0
	s_mov_b32 m0, s77
	v_lshl_add_u64 v[234:235], s[12:13], 0, v[134:135]
	ds_read_b128 v[190:193], v161 offset:32768
	ds_read_b128 v[194:197], v161 offset:33792
	ds_read_b128 v[202:205], v161 offset:34816
	ds_read_b128 v[206:209], v161 offset:35840
	ds_read_b128 v[210:213], v161 offset:36864
	ds_read_b128 v[214:217], v161 offset:37888
	ds_read_b128 v[218:221], v161 offset:38912
	ds_read_b128 v[222:225], v161 offset:39936
	global_load_lds_dwordx4 v[234:235], off sc1
	v_lshl_add_u64 v[234:235], s[12:13], 0, v[130:131]
	s_mov_b32 m0, s87
	s_nop 0
	global_load_lds_dwordx4 v[234:235], off sc1
	s_waitcnt vmcnt(8)
	s_waitcnt lgkmcnt(0)
	s_barrier
	s_setprio 1
	s_waitcnt lgkmcnt(0)
	v_mfma_f32_16x16x32_bf16 v[124:127], v[152:155], v[190:193], v[124:127]
	v_mfma_f32_16x16x32_bf16 v[120:123], v[166:169], v[190:193], v[120:123]
	v_mfma_f32_16x16x32_bf16 v[108:111], v[152:155], v[202:205], v[108:111]
	v_mfma_f32_16x16x32_bf16 v[104:107], v[166:169], v[202:205], v[104:107]
	v_mfma_f32_16x16x32_bf16 v[92:95], v[152:155], v[210:213], v[92:95]
	v_mfma_f32_16x16x32_bf16 v[88:91], v[166:169], v[210:213], v[88:91]
	v_mfma_f32_16x16x32_bf16 v[76:79], v[152:155], v[218:221], v[76:79]
	v_mfma_f32_16x16x32_bf16 v[72:75], v[166:169], v[218:221], v[72:75]
	v_mfma_f32_16x16x32_bf16 v[124:127], v[162:165], v[194:197], v[124:127]
	v_mfma_f32_16x16x32_bf16 v[120:123], v[170:173], v[194:197], v[120:123]
	v_mfma_f32_16x16x32_bf16 v[108:111], v[162:165], v[206:209], v[108:111]
	v_mfma_f32_16x16x32_bf16 v[104:107], v[170:173], v[206:209], v[104:107]
	v_mfma_f32_16x16x32_bf16 v[92:95], v[162:165], v[214:217], v[92:95]
	v_mfma_f32_16x16x32_bf16 v[88:91], v[170:173], v[214:217], v[88:91]
	v_mfma_f32_16x16x32_bf16 v[76:79], v[162:165], v[222:225], v[76:79]
	v_mfma_f32_16x16x32_bf16 v[72:75], v[170:173], v[222:225], v[72:75]
	s_setprio 0
	s_setprio 1
	v_mfma_f32_16x16x32_bf16 v[116:119], v[174:177], v[190:193], v[116:119]
	v_mfma_f32_16x16x32_bf16 v[112:115], v[182:185], v[190:193], v[112:115]
	v_mfma_f32_16x16x32_bf16 v[100:103], v[174:177], v[202:205], v[100:103]
	v_mfma_f32_16x16x32_bf16 v[96:99], v[182:185], v[202:205], v[96:99]
	v_mfma_f32_16x16x32_bf16 v[84:87], v[174:177], v[210:213], v[84:87]
	v_mfma_f32_16x16x32_bf16 v[80:83], v[182:185], v[210:213], v[80:83]
	v_mfma_f32_16x16x32_bf16 v[68:71], v[174:177], v[218:221], v[68:71]
	v_mfma_f32_16x16x32_bf16 v[64:67], v[182:185], v[218:221], v[64:67]
	v_mfma_f32_16x16x32_bf16 v[116:119], v[178:181], v[194:197], v[116:119]
	v_mfma_f32_16x16x32_bf16 v[112:115], v[186:189], v[194:197], v[112:115]
	v_mfma_f32_16x16x32_bf16 v[100:103], v[178:181], v[206:209], v[100:103]
	v_mfma_f32_16x16x32_bf16 v[96:99], v[186:189], v[206:209], v[96:99]
	v_mfma_f32_16x16x32_bf16 v[84:87], v[178:181], v[214:217], v[84:87]
	v_mfma_f32_16x16x32_bf16 v[80:83], v[186:189], v[214:217], v[80:83]
	v_mfma_f32_16x16x32_bf16 v[68:71], v[178:181], v[222:225], v[68:71]
	v_mfma_f32_16x16x32_bf16 v[64:67], v[186:189], v[222:225], v[64:67]
	s_setprio 0
	s_barrier
	s_add_i32 s12, vcc_hi, s3
	v_lshl_add_u64 v[198:199], v[198:199], 0, s[90:91]
	s_mov_b32 m0, s12
	ds_read_b128 v[190:193], v161 offset:49152
	ds_read_b128 v[194:197], v161 offset:50176
	ds_read_b128 v[202:205], v161 offset:51200
	ds_read_b128 v[206:209], v161 offset:52224
	ds_read_b128 v[210:213], v161 offset:53248
	ds_read_b128 v[214:217], v161 offset:54272
	ds_read_b128 v[218:221], v161 offset:55296
	ds_read_b128 v[222:225], v161 offset:56320
	global_load_lds_dwordx4 v[198:199], off sc1
	s_add_i32 m0, s12, 0x2000
	s_add_u32 s4, s4, 0x40080
	v_lshl_add_u64 v[198:199], v[226:227], 0, s[90:91]
	s_addc_u32 s5, s5, 0
	s_add_i32 s12, s14, s3
	global_load_lds_dwordx4 v[198:199], off sc1
	v_lshl_add_u64 v[198:199], s[4:5], 0, v[132:133]
	s_mov_b32 m0, s12
	s_nop 0
	global_load_lds_dwordx4 v[198:199], off sc1
	v_lshl_add_u64 v[198:199], s[4:5], 0, v[128:129]
	s_add_i32 m0, s12, 0x2000
	s_nop 0
	global_load_lds_dwordx4 v[198:199], off sc1
	v_lshl_add_u64 v[198:199], v[228:229], 0, s[90:91]
	s_mov_b32 m0, s97
	s_nop 0
	global_load_lds_dwordx4 v[198:199], off sc1
	v_lshl_add_u64 v[198:199], v[230:231], 0, s[90:91]
	s_mov_b32 m0, s99
	s_nop 0
	global_load_lds_dwordx4 v[198:199], off sc1
	s_waitcnt vmcnt(8)
	s_waitcnt lgkmcnt(0)
	s_barrier
	s_setprio 1
	s_waitcnt lgkmcnt(0)
	v_mfma_f32_16x16x32_bf16 v[60:63], v[152:155], v[190:193], v[60:63]
	v_mfma_f32_16x16x32_bf16 v[56:59], v[166:169], v[190:193], v[56:59]
	v_mfma_f32_16x16x32_bf16 v[44:47], v[152:155], v[202:205], v[44:47]
	v_mfma_f32_16x16x32_bf16 v[40:43], v[166:169], v[202:205], v[40:43]
	v_mfma_f32_16x16x32_bf16 v[28:31], v[152:155], v[210:213], v[28:31]
	v_mfma_f32_16x16x32_bf16 v[24:27], v[166:169], v[210:213], v[24:27]
	v_mfma_f32_16x16x32_bf16 v[12:15], v[152:155], v[218:221], v[12:15]
	v_mfma_f32_16x16x32_bf16 v[8:11], v[166:169], v[218:221], v[8:11]
	v_mfma_f32_16x16x32_bf16 v[60:63], v[162:165], v[194:197], v[60:63]
	v_mfma_f32_16x16x32_bf16 v[56:59], v[170:173], v[194:197], v[56:59]
	v_mfma_f32_16x16x32_bf16 v[44:47], v[162:165], v[206:209], v[44:47]
	v_mfma_f32_16x16x32_bf16 v[40:43], v[170:173], v[206:209], v[40:43]
	v_mfma_f32_16x16x32_bf16 v[28:31], v[162:165], v[214:217], v[28:31]
	v_mfma_f32_16x16x32_bf16 v[24:27], v[170:173], v[214:217], v[24:27]
	v_mfma_f32_16x16x32_bf16 v[12:15], v[162:165], v[222:225], v[12:15]
	v_mfma_f32_16x16x32_bf16 v[8:11], v[170:173], v[222:225], v[8:11]
	s_setprio 0
	s_setprio 1
	v_mfma_f32_16x16x32_bf16 v[52:55], v[174:177], v[190:193], v[52:55]
	v_mfma_f32_16x16x32_bf16 v[48:51], v[182:185], v[190:193], v[48:51]
	v_mfma_f32_16x16x32_bf16 v[36:39], v[174:177], v[202:205], v[36:39]
	v_mfma_f32_16x16x32_bf16 v[32:35], v[182:185], v[202:205], v[32:35]
	v_mfma_f32_16x16x32_bf16 v[20:23], v[174:177], v[210:213], v[20:23]
	v_mfma_f32_16x16x32_bf16 v[16:19], v[182:185], v[210:213], v[16:19]
	v_mfma_f32_16x16x32_bf16 v[4:7], v[174:177], v[218:221], v[4:7]
	v_mfma_f32_16x16x32_bf16 v[0:3], v[182:185], v[218:221], v[0:3]
	v_mfma_f32_16x16x32_bf16 v[52:55], v[178:181], v[194:197], v[52:55]
	v_mfma_f32_16x16x32_bf16 v[48:51], v[186:189], v[194:197], v[48:51]
	v_mfma_f32_16x16x32_bf16 v[36:39], v[178:181], v[206:209], v[36:39]
	v_mfma_f32_16x16x32_bf16 v[32:35], v[186:189], v[206:209], v[32:35]
	v_mfma_f32_16x16x32_bf16 v[20:23], v[178:181], v[214:217], v[20:23]
	v_mfma_f32_16x16x32_bf16 v[16:19], v[186:189], v[214:217], v[16:19]
	v_mfma_f32_16x16x32_bf16 v[4:7], v[178:181], v[222:225], v[4:7]
	v_mfma_f32_16x16x32_bf16 v[0:3], v[186:189], v[222:225], v[0:3]
	s_setprio 0
	s_barrier
	s_add_i32 vcc_lo, vcc_lo, 2
	s_add_u32 s0, s0, 0x100
	s_addc_u32 s1, s1, 0
	s_add_u32 s53, s53, 0x100
	s_addc_u32 s79, s79, 0
	s_cmp_gt_u32 vcc_lo, 13
	s_cbranch_scc0 .LBB0_180
	s_and_b64 vcc, exec, s[92:93]
	s_cbranch_vccnz .LBB0_184
	s_cmp_gt_i32 s11, 3
	s_mov_b64 s[0:1], -1
	s_cbranch_scc1 .LBB0_185

.LBB0_306:
	ds_read_b128 v[112:115], v213
	ds_read_b128 v[116:119], v213 offset:1024
	ds_read_b128 v[136:139], v213 offset:2048
	ds_read_b128 v[140:143], v213 offset:3072
	ds_read_b128 v[144:147], v243
	ds_read_b128 v[148:151], v243 offset:1024
	ds_read_b128 v[152:155], v243 offset:2048
	ds_read_b128 v[156:159], v243 offset:3072
	s_add_u32 s17, s8, 0xfffc0080
	s_addc_u32 s26, s9, -1
	s_cmp_eq_u32 s16, 12
	s_cselect_b32 s73, s11, s26
	s_cselect_b32 s72, s87, s17
	s_cselect_b32 s41, s89, vcc_hi
	s_cselect_b32 s40, s95, vcc_lo
	v_lshl_add_u64 v[192:193], s[8:9], 0, v[220:221]
	s_add_i32 m0, s55, 0xc000
	ds_read_b128 v[160:163], v244
	ds_read_b128 v[164:167], v244 offset:1024
	ds_read_b128 v[168:171], v244 offset:2048
	ds_read_b128 v[172:175], v244 offset:3072
	ds_read_b128 v[176:179], v244 offset:4096
	ds_read_b128 v[180:183], v244 offset:5120
	ds_read_b128 v[184:187], v244 offset:6144
	ds_read_b128 v[188:191], v244 offset:7168
	global_load_lds_dwordx4 v[192:193], off sc1
	v_lshl_add_u64 v[192:193], s[8:9], 0, v[222:223]
	s_add_i32 m0, s55, 0xe000
	s_nop 0
	global_load_lds_dwordx4 v[192:193], off sc1
	s_waitcnt vmcnt(8)
	s_waitcnt lgkmcnt(0)
	s_barrier
	s_setprio 1
	s_waitcnt lgkmcnt(0)
	v_mfma_f32_16x16x32_bf16 v[132:135], v[112:115], v[160:163], v[132:135]
	v_mfma_f32_16x16x32_bf16 v[124:127], v[136:139], v[160:163], v[124:127]
	v_mfma_f32_16x16x32_bf16 v[108:111], v[112:115], v[168:171], v[108:111]
	v_mfma_f32_16x16x32_bf16 v[100:103], v[136:139], v[168:171], v[100:103]
	v_mfma_f32_16x16x32_bf16 v[92:95], v[112:115], v[176:179], v[92:95]
	v_mfma_f32_16x16x32_bf16 v[84:87], v[136:139], v[176:179], v[84:87]
	v_mfma_f32_16x16x32_bf16 v[76:79], v[112:115], v[184:187], v[76:79]
	v_mfma_f32_16x16x32_bf16 v[68:71], v[136:139], v[184:187], v[68:71]
	v_mfma_f32_16x16x32_bf16 v[132:135], v[116:119], v[164:167], v[132:135]
	v_mfma_f32_16x16x32_bf16 v[124:127], v[140:143], v[164:167], v[124:127]
	v_mfma_f32_16x16x32_bf16 v[108:111], v[116:119], v[172:175], v[108:111]
	v_mfma_f32_16x16x32_bf16 v[100:103], v[140:143], v[172:175], v[100:103]
	v_mfma_f32_16x16x32_bf16 v[92:95], v[116:119], v[180:183], v[92:95]
	v_mfma_f32_16x16x32_bf16 v[84:87], v[140:143], v[180:183], v[84:87]
	v_mfma_f32_16x16x32_bf16 v[76:79], v[116:119], v[188:191], v[76:79]
	v_mfma_f32_16x16x32_bf16 v[68:71], v[140:143], v[188:191], v[68:71]
	s_setprio 0
	s_setprio 1
	v_mfma_f32_16x16x32_bf16 v[128:131], v[144:147], v[160:163], v[128:131]
	v_mfma_f32_16x16x32_bf16 v[120:123], v[152:155], v[160:163], v[120:123]
	v_mfma_f32_16x16x32_bf16 v[104:107], v[144:147], v[168:171], v[104:107]
	v_mfma_f32_16x16x32_bf16 v[96:99], v[152:155], v[168:171], v[96:99]
	v_mfma_f32_16x16x32_bf16 v[88:91], v[144:147], v[176:179], v[88:91]
	v_mfma_f32_16x16x32_bf16 v[80:83], v[152:155], v[176:179], v[80:83]
	v_mfma_f32_16x16x32_bf16 v[72:75], v[144:147], v[184:187], v[72:75]
	v_mfma_f32_16x16x32_bf16 v[64:67], v[152:155], v[184:187], v[64:67]
	v_mfma_f32_16x16x32_bf16 v[128:131], v[148:151], v[164:167], v[128:131]
	v_mfma_f32_16x16x32_bf16 v[120:123], v[156:159], v[164:167], v[120:123]
	v_mfma_f32_16x16x32_bf16 v[104:107], v[148:151], v[172:175], v[104:107]
	v_mfma_f32_16x16x32_bf16 v[96:99], v[156:159], v[172:175], v[96:99]
	v_mfma_f32_16x16x32_bf16 v[88:91], v[148:151], v[180:183], v[88:91]
	v_mfma_f32_16x16x32_bf16 v[80:83], v[156:159], v[180:183], v[80:83]
	v_mfma_f32_16x16x32_bf16 v[72:75], v[148:151], v[188:191], v[72:75]
	v_mfma_f32_16x16x32_bf16 v[64:67], v[156:159], v[188:191], v[64:67]
	s_setprio 0
	s_barrier
	s_add_i32 s17, s3, s53
	v_lshl_add_u64 v[192:193], s[40:41], 0, v[204:205]
	s_mov_b32 m0, s17
	ds_read_b128 v[160:163], v244 offset:16384
	ds_read_b128 v[164:167], v244 offset:17408
	ds_read_b128 v[168:171], v244 offset:18432
	ds_read_b128 v[172:175], v244 offset:19456
	ds_read_b128 v[176:179], v244 offset:20480
	ds_read_b128 v[180:183], v244 offset:21504
	ds_read_b128 v[184:187], v244 offset:22528
	ds_read_b128 v[188:191], v244 offset:23552
	global_load_lds_dwordx4 v[192:193], off sc1
	s_add_i32 m0, s17, 0x2000
	s_add_u32 s26, s40, 0x40000
	v_lshl_add_u64 v[194:195], s[40:41], 0, v[208:209]
	s_addc_u32 s27, s41, 0
	s_add_i32 s17, s33, s53
	global_load_lds_dwordx4 v[194:195], off sc1
	v_lshl_add_u64 v[196:197], s[26:27], 0, v[204:205]
	s_mov_b32 m0, s17
	v_lshl_add_u64 v[198:199], s[72:73], 0, v[206:207]
	global_load_lds_dwordx4 v[196:197], off sc1
	v_lshl_add_u64 v[196:197], s[26:27], 0, v[208:209]
	s_add_i32 m0, s17, 0x2000
	s_nop 0
	global_load_lds_dwordx4 v[196:197], off sc1
	v_lshl_add_u64 v[196:197], s[72:73], 0, v[202:203]
	s_mov_b32 m0, s55
	s_nop 0
	global_load_lds_dwordx4 v[196:197], off sc1
	s_mov_b32 m0, s63
	s_nop 0
	global_load_lds_dwordx4 v[198:199], off sc1
	s_waitcnt vmcnt(8)
	s_waitcnt lgkmcnt(0)
	s_barrier
	s_setprio 1
	s_waitcnt lgkmcnt(0)
	v_mfma_f32_16x16x32_bf16 v[60:63], v[112:115], v[160:163], v[60:63]
	v_mfma_f32_16x16x32_bf16 v[52:55], v[136:139], v[160:163], v[52:55]
	v_mfma_f32_16x16x32_bf16 v[44:47], v[112:115], v[168:171], v[44:47]
	v_mfma_f32_16x16x32_bf16 v[36:39], v[136:139], v[168:171], v[36:39]
	v_mfma_f32_16x16x32_bf16 v[28:31], v[112:115], v[176:179], v[28:31]
	v_mfma_f32_16x16x32_bf16 v[20:23], v[136:139], v[176:179], v[20:23]
	v_mfma_f32_16x16x32_bf16 v[12:15], v[112:115], v[184:187], v[12:15]
	v_mfma_f32_16x16x32_bf16 v[4:7], v[136:139], v[184:187], v[4:7]
	v_mfma_f32_16x16x32_bf16 v[60:63], v[116:119], v[164:167], v[60:63]
	v_mfma_f32_16x16x32_bf16 v[52:55], v[140:143], v[164:167], v[52:55]
	v_mfma_f32_16x16x32_bf16 v[44:47], v[116:119], v[172:175], v[44:47]
	v_mfma_f32_16x16x32_bf16 v[36:39], v[140:143], v[172:175], v[36:39]
	v_mfma_f32_16x16x32_bf16 v[28:31], v[116:119], v[180:183], v[28:31]
	v_mfma_f32_16x16x32_bf16 v[20:23], v[140:143], v[180:183], v[20:23]
	v_mfma_f32_16x16x32_bf16 v[12:15], v[116:119], v[188:191], v[12:15]
	v_mfma_f32_16x16x32_bf16 v[4:7], v[140:143], v[188:191], v[4:7]
	s_setprio 0
	s_setprio 1
	v_mfma_f32_16x16x32_bf16 v[56:59], v[144:147], v[160:163], v[56:59]
	v_mfma_f32_16x16x32_bf16 v[48:51], v[152:155], v[160:163], v[48:51]
	v_mfma_f32_16x16x32_bf16 v[40:43], v[144:147], v[168:171], v[40:43]
	v_mfma_f32_16x16x32_bf16 v[32:35], v[152:155], v[168:171], v[32:35]
	v_mfma_f32_16x16x32_bf16 v[24:27], v[144:147], v[176:179], v[24:27]
	v_mfma_f32_16x16x32_bf16 v[16:19], v[152:155], v[176:179], v[16:19]
	v_mfma_f32_16x16x32_bf16 v[8:11], v[144:147], v[184:187], v[8:11]
	v_mfma_f32_16x16x32_bf16 v[0:3], v[152:155], v[184:187], v[0:3]
	v_mfma_f32_16x16x32_bf16 v[56:59], v[148:151], v[164:167], v[56:59]
	v_mfma_f32_16x16x32_bf16 v[48:51], v[156:159], v[164:167], v[48:51]
	v_mfma_f32_16x16x32_bf16 v[40:43], v[148:151], v[172:175], v[40:43]
	v_mfma_f32_16x16x32_bf16 v[32:35], v[156:159], v[172:175], v[32:35]
	v_mfma_f32_16x16x32_bf16 v[24:27], v[148:151], v[180:183], v[24:27]
	v_mfma_f32_16x16x32_bf16 v[16:19], v[156:159], v[180:183], v[16:19]
	v_mfma_f32_16x16x32_bf16 v[8:11], v[148:151], v[188:191], v[8:11]
	v_mfma_f32_16x16x32_bf16 v[0:3], v[156:159], v[188:191], v[0:3]
	s_setprio 0
	s_barrier
	s_add_i32 s17, 0, 0x18000
	s_add_i32 s28, 0, 0x1c000
	v_add_u32_e32 v140, s17, v235
	v_add_u32_e32 v156, s28, v235
	ds_read_b128 v[112:115], v140
	ds_read_b128 v[116:119], v140 offset:1024
	ds_read_b128 v[136:139], v140 offset:2048
	ds_read_b128 v[140:143], v140 offset:3072
	ds_read_b128 v[144:147], v156
	ds_read_b128 v[148:151], v156 offset:1024
	ds_read_b128 v[152:155], v156 offset:2048
	ds_read_b128 v[156:159], v156 offset:3072
	s_add_u32 s26, s72, 0x40000
	s_addc_u32 s27, s73, 0
	s_mov_b32 m0, s74
	v_lshl_add_u64 v[228:229], s[26:27], 0, v[202:203]
	ds_read_b128 v[160:163], v244 offset:32768
	ds_read_b128 v[164:167], v244 offset:33792
	ds_read_b128 v[168:171], v244 offset:34816
	ds_read_b128 v[172:175], v244 offset:35840
	ds_read_b128 v[176:179], v244 offset:36864
	ds_read_b128 v[180:183], v244 offset:37888
	ds_read_b128 v[184:187], v244 offset:38912
	ds_read_b128 v[188:191], v244 offset:39936
	global_load_lds_dwordx4 v[228:229], off sc1
	v_lshl_add_u64 v[228:229], s[26:27], 0, v[206:207]
	s_mov_b32 m0, s76
	s_nop 0
	global_load_lds_dwordx4 v[228:229], off sc1
	s_waitcnt vmcnt(8)
	s_waitcnt lgkmcnt(0)
	s_barrier
	s_setprio 1
	s_waitcnt lgkmcnt(0)
	v_mfma_f32_16x16x32_bf16 v[132:135], v[112:115], v[160:163], v[132:135]
	v_mfma_f32_16x16x32_bf16 v[124:127], v[136:139], v[160:163], v[124:127]
	v_mfma_f32_16x16x32_bf16 v[108:111], v[112:115], v[168:171], v[108:111]
	v_mfma_f32_16x16x32_bf16 v[100:103], v[136:139], v[168:171], v[100:103]
	v_mfma_f32_16x16x32_bf16 v[92:95], v[112:115], v[176:179], v[92:95]
	v_mfma_f32_16x16x32_bf16 v[84:87], v[136:139], v[176:179], v[84:87]
	v_mfma_f32_16x16x32_bf16 v[76:79], v[112:115], v[184:187], v[76:79]
	v_mfma_f32_16x16x32_bf16 v[68:71], v[136:139], v[184:187], v[68:71]
	v_mfma_f32_16x16x32_bf16 v[132:135], v[116:119], v[164:167], v[132:135]
	v_mfma_f32_16x16x32_bf16 v[124:127], v[140:143], v[164:167], v[124:127]
	v_mfma_f32_16x16x32_bf16 v[108:111], v[116:119], v[172:175], v[108:111]
	v_mfma_f32_16x16x32_bf16 v[100:103], v[140:143], v[172:175], v[100:103]
	v_mfma_f32_16x16x32_bf16 v[92:95], v[116:119], v[180:183], v[92:95]
	v_mfma_f32_16x16x32_bf16 v[84:87], v[140:143], v[180:183], v[84:87]
	v_mfma_f32_16x16x32_bf16 v[76:79], v[116:119], v[188:191], v[76:79]
	v_mfma_f32_16x16x32_bf16 v[68:71], v[140:143], v[188:191], v[68:71]
	s_setprio 0
	s_setprio 1
	v_mfma_f32_16x16x32_bf16 v[128:131], v[144:147], v[160:163], v[128:131]
	v_mfma_f32_16x16x32_bf16 v[120:123], v[152:155], v[160:163], v[120:123]
	v_mfma_f32_16x16x32_bf16 v[104:107], v[144:147], v[168:171], v[104:107]
	v_mfma_f32_16x16x32_bf16 v[96:99], v[152:155], v[168:171], v[96:99]
	v_mfma_f32_16x16x32_bf16 v[88:91], v[144:147], v[176:179], v[88:91]
	v_mfma_f32_16x16x32_bf16 v[80:83], v[152:155], v[176:179], v[80:83]
	v_mfma_f32_16x16x32_bf16 v[72:75], v[144:147], v[184:187], v[72:75]
	v_mfma_f32_16x16x32_bf16 v[64:67], v[152:155], v[184:187], v[64:67]
	v_mfma_f32_16x16x32_bf16 v[128:131], v[148:151], v[164:167], v[128:131]
	v_mfma_f32_16x16x32_bf16 v[120:123], v[156:159], v[164:167], v[120:123]
	v_mfma_f32_16x16x32_bf16 v[104:107], v[148:151], v[172:175], v[104:107]
	v_mfma_f32_16x16x32_bf16 v[96:99], v[156:159], v[172:175], v[96:99]
	v_mfma_f32_16x16x32_bf16 v[88:91], v[148:151], v[180:183], v[88:91]
	v_mfma_f32_16x16x32_bf16 v[80:83], v[156:159], v[180:183], v[80:83]
	v_mfma_f32_16x16x32_bf16 v[72:75], v[148:151], v[188:191], v[72:75]
	v_mfma_f32_16x16x32_bf16 v[64:67], v[156:159], v[188:191], v[64:67]
	s_setprio 0
	s_barrier
	s_add_i32 s17, s17, s53
	v_lshl_add_u64 v[192:193], v[192:193], 0, s[20:21]
	s_mov_b32 m0, s17
	ds_read_b128 v[160:163], v244 offset:49152
	ds_read_b128 v[164:167], v244 offset:50176
	ds_read_b128 v[168:171], v244 offset:51200
	ds_read_b128 v[172:175], v244 offset:52224
	ds_read_b128 v[176:179], v244 offset:53248
	ds_read_b128 v[180:183], v244 offset:54272
	ds_read_b128 v[184:187], v244 offset:55296
	ds_read_b128 v[188:191], v244 offset:56320
	global_load_lds_dwordx4 v[192:193], off sc1
	s_add_i32 m0, s17, 0x2000
	s_add_u32 s26, s40, 0x40080
	v_lshl_add_u64 v[192:193], v[194:195], 0, s[20:21]
	s_addc_u32 s27, s41, 0
	s_add_i32 s17, s28, s53
	global_load_lds_dwordx4 v[192:193], off sc1
	v_lshl_add_u64 v[192:193], s[26:27], 0, v[204:205]
	s_mov_b32 m0, s17
	s_nop 0
	global_load_lds_dwordx4 v[192:193], off sc1
	v_lshl_add_u64 v[192:193], s[26:27], 0, v[208:209]
	s_add_i32 m0, s17, 0x2000
	s_nop 0
	global_load_lds_dwordx4 v[192:193], off sc1
	v_lshl_add_u64 v[192:193], v[196:197], 0, s[20:21]
	s_mov_b32 m0, s78
	s_nop 0
	global_load_lds_dwordx4 v[192:193], off sc1
	v_lshl_add_u64 v[192:193], v[198:199], 0, s[20:21]
	s_mov_b32 m0, s79
	s_nop 0
	global_load_lds_dwordx4 v[192:193], off sc1
	s_waitcnt vmcnt(8)
	s_waitcnt lgkmcnt(0)
	s_barrier
	s_setprio 1
	s_waitcnt lgkmcnt(0)
	v_mfma_f32_16x16x32_bf16 v[60:63], v[112:115], v[160:163], v[60:63]
	v_mfma_f32_16x16x32_bf16 v[52:55], v[136:139], v[160:163], v[52:55]
	v_mfma_f32_16x16x32_bf16 v[44:47], v[112:115], v[168:171], v[44:47]
	v_mfma_f32_16x16x32_bf16 v[36:39], v[136:139], v[168:171], v[36:39]
	v_mfma_f32_16x16x32_bf16 v[28:31], v[112:115], v[176:179], v[28:31]
	v_mfma_f32_16x16x32_bf16 v[20:23], v[136:139], v[176:179], v[20:23]
	v_mfma_f32_16x16x32_bf16 v[12:15], v[112:115], v[184:187], v[12:15]
	v_mfma_f32_16x16x32_bf16 v[4:7], v[136:139], v[184:187], v[4:7]
	v_mfma_f32_16x16x32_bf16 v[60:63], v[116:119], v[164:167], v[60:63]
	v_mfma_f32_16x16x32_bf16 v[52:55], v[140:143], v[164:167], v[52:55]
	v_mfma_f32_16x16x32_bf16 v[44:47], v[116:119], v[172:175], v[44:47]
	v_mfma_f32_16x16x32_bf16 v[36:39], v[140:143], v[172:175], v[36:39]
	v_mfma_f32_16x16x32_bf16 v[28:31], v[116:119], v[180:183], v[28:31]
	v_mfma_f32_16x16x32_bf16 v[20:23], v[140:143], v[180:183], v[20:23]
	v_mfma_f32_16x16x32_bf16 v[12:15], v[116:119], v[188:191], v[12:15]
	v_mfma_f32_16x16x32_bf16 v[4:7], v[140:143], v[188:191], v[4:7]
	s_setprio 0
	s_setprio 1
	v_mfma_f32_16x16x32_bf16 v[56:59], v[144:147], v[160:163], v[56:59]
	v_mfma_f32_16x16x32_bf16 v[48:51], v[152:155], v[160:163], v[48:51]
	v_mfma_f32_16x16x32_bf16 v[40:43], v[144:147], v[168:171], v[40:43]
	v_mfma_f32_16x16x32_bf16 v[32:35], v[152:155], v[168:171], v[32:35]
	v_mfma_f32_16x16x32_bf16 v[24:27], v[144:147], v[176:179], v[24:27]
	v_mfma_f32_16x16x32_bf16 v[16:19], v[152:155], v[176:179], v[16:19]
	v_mfma_f32_16x16x32_bf16 v[8:11], v[144:147], v[184:187], v[8:11]
	v_mfma_f32_16x16x32_bf16 v[0:3], v[152:155], v[184:187], v[0:3]
	v_mfma_f32_16x16x32_bf16 v[56:59], v[148:151], v[164:167], v[56:59]
	v_mfma_f32_16x16x32_bf16 v[48:51], v[156:159], v[164:167], v[48:51]
	v_mfma_f32_16x16x32_bf16 v[40:43], v[148:151], v[172:175], v[40:43]
	v_mfma_f32_16x16x32_bf16 v[32:35], v[156:159], v[172:175], v[32:35]
	v_mfma_f32_16x16x32_bf16 v[24:27], v[148:151], v[180:183], v[24:27]
	v_mfma_f32_16x16x32_bf16 v[16:19], v[156:159], v[180:183], v[16:19]
	v_mfma_f32_16x16x32_bf16 v[8:11], v[148:151], v[188:191], v[8:11]
	v_mfma_f32_16x16x32_bf16 v[0:3], v[156:159], v[188:191], v[0:3]
	s_setprio 0
	s_barrier
	s_add_i32 s16, s16, 2
	s_add_u32 s8, s8, 0x100
	s_addc_u32 s9, s9, 0
	s_add_u32 vcc_lo, vcc_lo, 0x100
	s_addc_u32 vcc_hi, vcc_hi, 0
	s_cmp_gt_u32 s16, 13
	s_cbranch_scc0 .LBB0_306
	s_and_b64 vcc, exec, s[22:23]
	s_cbranch_vccnz .LBB0_311
	s_lshl_b32 s87, s10, 7
	s_cmp_gt_i32 s10, 7
	s_mov_b64 s[8:9], -1
	s_cbranch_scc1 .LBB0_312

.LBB0_495:
	v_add_u32_e32 v147, s53, v145
	ds_read_b128 v[148:151], v147
	ds_read_b128 v[152:155], v147 offset:1024
	ds_read_b128 v[156:159], v147 offset:2048
	ds_read_b128 v[160:163], v147 offset:3072
	v_add_u32_e32 v147, s54, v145
	s_add_u32 s34, s16, s30
	ds_read_b128 v[164:167], v147
	ds_read_b128 v[172:175], v147 offset:1024
	ds_read_b128 v[176:179], v147 offset:2048
	ds_read_b128 v[180:183], v147 offset:3072
	s_addc_u32 s35, s17, s31
	s_add_u32 s34, s34, 0x100
	s_addc_u32 s35, s35, 0
	s_add_u32 s59, s27, s30
	s_addc_u32 s60, s55, s31
	s_cmpk_eq_i32 s30, 0xf00
	s_cselect_b32 s37, s21, s35
	s_cselect_b32 s36, s23, s34
	s_cselect_b32 s35, s56, s60
	s_cselect_b32 s34, s57, s59
	v_lshl_add_u64 v[168:169], v[140:141], 0, s[30:31]
	s_add_i32 m0, s40, 0xc000
	ds_read_b128 v[184:187], v146
	ds_read_b128 v[188:191], v146 offset:1024
	ds_read_b128 v[192:195], v146 offset:2048
	ds_read_b128 v[196:199], v146 offset:3072
	ds_read_b128 v[202:205], v146 offset:4096
	ds_read_b128 v[206:209], v146 offset:5120
	ds_read_b128 v[210:213], v146 offset:6144
	ds_read_b128 v[214:217], v146 offset:7168
	global_load_lds_dwordx4 v[168:169], off sc1
	v_lshl_add_u64 v[168:169], v[142:143], 0, s[30:31]
	s_add_i32 m0, s40, 0xe000
	s_nop 0
	global_load_lds_dwordx4 v[168:169], off sc1
	s_waitcnt vmcnt(8)
	s_waitcnt lgkmcnt(0)
	s_barrier
	s_setprio 1
	s_waitcnt lgkmcnt(0)
	v_mfma_f32_16x16x32_bf16 v[124:127], v[148:151], v[184:187], v[124:127]
	v_mfma_f32_16x16x32_bf16 v[120:123], v[156:159], v[184:187], v[120:123]
	v_mfma_f32_16x16x32_bf16 v[108:111], v[148:151], v[192:195], v[108:111]
	v_mfma_f32_16x16x32_bf16 v[104:107], v[156:159], v[192:195], v[104:107]
	v_mfma_f32_16x16x32_bf16 v[92:95], v[148:151], v[202:205], v[92:95]
	v_mfma_f32_16x16x32_bf16 v[88:91], v[156:159], v[202:205], v[88:91]
	v_mfma_f32_16x16x32_bf16 v[76:79], v[148:151], v[210:213], v[76:79]
	v_mfma_f32_16x16x32_bf16 v[72:75], v[156:159], v[210:213], v[72:75]
	v_mfma_f32_16x16x32_bf16 v[124:127], v[152:155], v[188:191], v[124:127]
	v_mfma_f32_16x16x32_bf16 v[120:123], v[160:163], v[188:191], v[120:123]
	v_mfma_f32_16x16x32_bf16 v[108:111], v[152:155], v[196:199], v[108:111]
	v_mfma_f32_16x16x32_bf16 v[104:107], v[160:163], v[196:199], v[104:107]
	v_mfma_f32_16x16x32_bf16 v[92:95], v[152:155], v[206:209], v[92:95]
	v_mfma_f32_16x16x32_bf16 v[88:91], v[160:163], v[206:209], v[88:91]
	v_mfma_f32_16x16x32_bf16 v[76:79], v[152:155], v[214:217], v[76:79]
	v_mfma_f32_16x16x32_bf16 v[72:75], v[160:163], v[214:217], v[72:75]
	s_setprio 0
	s_setprio 1
	v_mfma_f32_16x16x32_bf16 v[116:119], v[164:167], v[184:187], v[116:119]
	v_mfma_f32_16x16x32_bf16 v[112:115], v[176:179], v[184:187], v[112:115]
	v_mfma_f32_16x16x32_bf16 v[100:103], v[164:167], v[192:195], v[100:103]
	v_mfma_f32_16x16x32_bf16 v[96:99], v[176:179], v[192:195], v[96:99]
	v_mfma_f32_16x16x32_bf16 v[84:87], v[164:167], v[202:205], v[84:87]
	v_mfma_f32_16x16x32_bf16 v[80:83], v[176:179], v[202:205], v[80:83]
	v_mfma_f32_16x16x32_bf16 v[68:71], v[164:167], v[210:213], v[68:71]
	v_mfma_f32_16x16x32_bf16 v[64:67], v[176:179], v[210:213], v[64:67]
	v_mfma_f32_16x16x32_bf16 v[116:119], v[172:175], v[188:191], v[116:119]
	v_mfma_f32_16x16x32_bf16 v[112:115], v[180:183], v[188:191], v[112:115]
	v_mfma_f32_16x16x32_bf16 v[100:103], v[172:175], v[196:199], v[100:103]
	v_mfma_f32_16x16x32_bf16 v[96:99], v[180:183], v[196:199], v[96:99]
	v_mfma_f32_16x16x32_bf16 v[84:87], v[172:175], v[206:209], v[84:87]
	v_mfma_f32_16x16x32_bf16 v[80:83], v[180:183], v[206:209], v[80:83]
	v_mfma_f32_16x16x32_bf16 v[68:71], v[172:175], v[214:217], v[68:71]
	v_mfma_f32_16x16x32_bf16 v[64:67], v[180:183], v[214:217], v[64:67]
	s_setprio 0
	s_barrier
	s_add_i32 s59, s53, s39
	v_lshl_add_u64 v[168:169], s[34:35], 0, v[128:129]
	s_mov_b32 m0, s59
	ds_read_b128 v[184:187], v146 offset:16384
	ds_read_b128 v[188:191], v146 offset:17408
	ds_read_b128 v[192:195], v146 offset:18432
	ds_read_b128 v[196:199], v146 offset:19456
	ds_read_b128 v[202:205], v146 offset:20480
	ds_read_b128 v[206:209], v146 offset:21504
	ds_read_b128 v[210:213], v146 offset:22528
	ds_read_b128 v[214:217], v146 offset:23552
	global_load_lds_dwordx4 v[168:169], off sc1
	s_add_i32 m0, s59, 0x2000
	s_add_u32 s60, s34, 0x80000
	v_lshl_add_u64 v[218:219], s[34:35], 0, v[130:131]
	s_addc_u32 s61, s35, 0
	s_add_i32 s59, s54, s39
	global_load_lds_dwordx4 v[218:219], off sc1
	v_lshl_add_u64 v[220:221], s[60:61], 0, v[128:129]
	s_mov_b32 m0, s59
	v_lshl_add_u64 v[222:223], s[36:37], 0, v[130:131]
	global_load_lds_dwordx4 v[220:221], off sc1
	v_lshl_add_u64 v[220:221], s[60:61], 0, v[130:131]
	s_add_i32 m0, s59, 0x2000
	s_nop 0
	global_load_lds_dwordx4 v[220:221], off sc1
	v_lshl_add_u64 v[220:221], s[36:37], 0, v[128:129]
	s_mov_b32 m0, s40
	s_nop 0
	global_load_lds_dwordx4 v[220:221], off sc1
	s_mov_b32 m0, s41
	s_nop 0
	global_load_lds_dwordx4 v[222:223], off sc1
	s_waitcnt vmcnt(8)
	s_waitcnt lgkmcnt(0)
	s_barrier
	s_setprio 1
	s_waitcnt lgkmcnt(0)
	v_mfma_f32_16x16x32_bf16 v[60:63], v[148:151], v[184:187], v[60:63]
	v_mfma_f32_16x16x32_bf16 v[56:59], v[156:159], v[184:187], v[56:59]
	v_mfma_f32_16x16x32_bf16 v[44:47], v[148:151], v[192:195], v[44:47]
	v_mfma_f32_16x16x32_bf16 v[40:43], v[156:159], v[192:195], v[40:43]
	v_mfma_f32_16x16x32_bf16 v[28:31], v[148:151], v[202:205], v[28:31]
	v_mfma_f32_16x16x32_bf16 v[24:27], v[156:159], v[202:205], v[24:27]
	v_mfma_f32_16x16x32_bf16 v[12:15], v[148:151], v[210:213], v[12:15]
	v_mfma_f32_16x16x32_bf16 v[8:11], v[156:159], v[210:213], v[8:11]
	v_mfma_f32_16x16x32_bf16 v[60:63], v[152:155], v[188:191], v[60:63]
	v_mfma_f32_16x16x32_bf16 v[56:59], v[160:163], v[188:191], v[56:59]
	v_mfma_f32_16x16x32_bf16 v[44:47], v[152:155], v[196:199], v[44:47]
	v_mfma_f32_16x16x32_bf16 v[40:43], v[160:163], v[196:199], v[40:43]
	v_mfma_f32_16x16x32_bf16 v[28:31], v[152:155], v[206:209], v[28:31]
	v_mfma_f32_16x16x32_bf16 v[24:27], v[160:163], v[206:209], v[24:27]
	v_mfma_f32_16x16x32_bf16 v[12:15], v[152:155], v[214:217], v[12:15]
	v_mfma_f32_16x16x32_bf16 v[8:11], v[160:163], v[214:217], v[8:11]
	s_setprio 0
	s_setprio 1
	v_mfma_f32_16x16x32_bf16 v[52:55], v[164:167], v[184:187], v[52:55]
	v_mfma_f32_16x16x32_bf16 v[48:51], v[176:179], v[184:187], v[48:51]
	v_mfma_f32_16x16x32_bf16 v[36:39], v[164:167], v[192:195], v[36:39]
	v_mfma_f32_16x16x32_bf16 v[32:35], v[176:179], v[192:195], v[32:35]
	v_mfma_f32_16x16x32_bf16 v[20:23], v[164:167], v[202:205], v[20:23]
	v_mfma_f32_16x16x32_bf16 v[16:19], v[176:179], v[202:205], v[16:19]
	v_mfma_f32_16x16x32_bf16 v[4:7], v[164:167], v[210:213], v[4:7]
	v_mfma_f32_16x16x32_bf16 v[0:3], v[176:179], v[210:213], v[0:3]
	v_mfma_f32_16x16x32_bf16 v[52:55], v[172:175], v[188:191], v[52:55]
	v_mfma_f32_16x16x32_bf16 v[48:51], v[180:183], v[188:191], v[48:51]
	v_mfma_f32_16x16x32_bf16 v[36:39], v[172:175], v[196:199], v[36:39]
	v_mfma_f32_16x16x32_bf16 v[32:35], v[180:183], v[196:199], v[32:35]
	v_mfma_f32_16x16x32_bf16 v[20:23], v[172:175], v[206:209], v[20:23]
	v_mfma_f32_16x16x32_bf16 v[16:19], v[180:183], v[206:209], v[16:19]
	v_mfma_f32_16x16x32_bf16 v[4:7], v[172:175], v[214:217], v[4:7]
	v_mfma_f32_16x16x32_bf16 v[0:3], v[180:183], v[214:217], v[0:3]
	s_setprio 0
	s_barrier
	s_add_i32 s59, 0, 0x18000
	v_add_u32_e32 v147, s59, v145
	s_add_i32 s60, 0, 0x1c000
	ds_read_b128 v[148:151], v147
	ds_read_b128 v[152:155], v147 offset:1024
	ds_read_b128 v[156:159], v147 offset:2048
	ds_read_b128 v[160:163], v147 offset:3072
	v_add_u32_e32 v147, s60, v145
	ds_read_b128 v[164:167], v147
	ds_read_b128 v[172:175], v147 offset:1024
	ds_read_b128 v[176:179], v147 offset:2048
	ds_read_b128 v[180:183], v147 offset:3072
	s_add_u32 s36, s36, 0x80000
	s_addc_u32 s37, s37, 0
	s_mov_b32 m0, s43
	v_lshl_add_u64 v[224:225], s[36:37], 0, v[128:129]
	ds_read_b128 v[184:187], v146 offset:32768
	ds_read_b128 v[188:191], v146 offset:33792
	ds_read_b128 v[192:195], v146 offset:34816
	ds_read_b128 v[196:199], v146 offset:35840
	ds_read_b128 v[202:205], v146 offset:36864
	ds_read_b128 v[206:209], v146 offset:37888
	ds_read_b128 v[210:213], v146 offset:38912
	ds_read_b128 v[214:217], v146 offset:39936
	global_load_lds_dwordx4 v[224:225], off sc1
	v_lshl_add_u64 v[224:225], s[36:37], 0, v[130:131]
	s_mov_b32 m0, s48
	s_nop 0
	global_load_lds_dwordx4 v[224:225], off sc1
	s_waitcnt vmcnt(8)
	s_waitcnt lgkmcnt(0)
	s_barrier
	s_setprio 1
	s_waitcnt lgkmcnt(0)
	v_mfma_f32_16x16x32_bf16 v[124:127], v[148:151], v[184:187], v[124:127]
	v_mfma_f32_16x16x32_bf16 v[120:123], v[156:159], v[184:187], v[120:123]
	v_mfma_f32_16x16x32_bf16 v[108:111], v[148:151], v[192:195], v[108:111]
	v_mfma_f32_16x16x32_bf16 v[104:107], v[156:159], v[192:195], v[104:107]
	v_mfma_f32_16x16x32_bf16 v[92:95], v[148:151], v[202:205], v[92:95]
	v_mfma_f32_16x16x32_bf16 v[88:91], v[156:159], v[202:205], v[88:91]
	v_mfma_f32_16x16x32_bf16 v[76:79], v[148:151], v[210:213], v[76:79]
	v_mfma_f32_16x16x32_bf16 v[72:75], v[156:159], v[210:213], v[72:75]
	v_mfma_f32_16x16x32_bf16 v[124:127], v[152:155], v[188:191], v[124:127]
	v_mfma_f32_16x16x32_bf16 v[120:123], v[160:163], v[188:191], v[120:123]
	v_mfma_f32_16x16x32_bf16 v[108:111], v[152:155], v[196:199], v[108:111]
	v_mfma_f32_16x16x32_bf16 v[104:107], v[160:163], v[196:199], v[104:107]
	v_mfma_f32_16x16x32_bf16 v[92:95], v[152:155], v[206:209], v[92:95]
	v_mfma_f32_16x16x32_bf16 v[88:91], v[160:163], v[206:209], v[88:91]
	v_mfma_f32_16x16x32_bf16 v[76:79], v[152:155], v[214:217], v[76:79]
	v_mfma_f32_16x16x32_bf16 v[72:75], v[160:163], v[214:217], v[72:75]
	s_setprio 0
	s_setprio 1
	v_mfma_f32_16x16x32_bf16 v[116:119], v[164:167], v[184:187], v[116:119]
	v_mfma_f32_16x16x32_bf16 v[112:115], v[176:179], v[184:187], v[112:115]
	v_mfma_f32_16x16x32_bf16 v[100:103], v[164:167], v[192:195], v[100:103]
	v_mfma_f32_16x16x32_bf16 v[96:99], v[176:179], v[192:195], v[96:99]
	v_mfma_f32_16x16x32_bf16 v[84:87], v[164:167], v[202:205], v[84:87]
	v_mfma_f32_16x16x32_bf16 v[80:83], v[176:179], v[202:205], v[80:83]
	v_mfma_f32_16x16x32_bf16 v[68:71], v[164:167], v[210:213], v[68:71]
	v_mfma_f32_16x16x32_bf16 v[64:67], v[176:179], v[210:213], v[64:67]
	v_mfma_f32_16x16x32_bf16 v[116:119], v[172:175], v[188:191], v[116:119]
	v_mfma_f32_16x16x32_bf16 v[112:115], v[180:183], v[188:191], v[112:115]
	v_mfma_f32_16x16x32_bf16 v[100:103], v[172:175], v[196:199], v[100:103]
	v_mfma_f32_16x16x32_bf16 v[96:99], v[180:183], v[196:199], v[96:99]
	v_mfma_f32_16x16x32_bf16 v[84:87], v[172:175], v[206:209], v[84:87]
	v_mfma_f32_16x16x32_bf16 v[80:83], v[180:183], v[206:209], v[80:83]
	v_mfma_f32_16x16x32_bf16 v[68:71], v[172:175], v[214:217], v[68:71]
	v_mfma_f32_16x16x32_bf16 v[64:67], v[180:183], v[214:217], v[64:67]
	s_setprio 0
	s_barrier
	s_add_i32 s36, s59, s39
	v_lshl_add_u64 v[168:169], v[168:169], 0, s[18:19]
	s_mov_b32 m0, s36
	ds_read_b128 v[184:187], v146 offset:49152
	ds_read_b128 v[188:191], v146 offset:50176
	ds_read_b128 v[192:195], v146 offset:51200
	ds_read_b128 v[196:199], v146 offset:52224
	ds_read_b128 v[202:205], v146 offset:53248
	ds_read_b128 v[206:209], v146 offset:54272
	ds_read_b128 v[210:213], v146 offset:55296
	ds_read_b128 v[214:217], v146 offset:56320
	global_load_lds_dwordx4 v[168:169], off sc1
	s_add_i32 m0, s36, 0x2000
	s_add_u32 s34, s34, 0x80080
	v_lshl_add_u64 v[168:169], v[218:219], 0, s[18:19]
	s_addc_u32 s35, s35, 0
	s_add_i32 s36, s60, s39
	global_load_lds_dwordx4 v[168:169], off sc1
	v_lshl_add_u64 v[168:169], s[34:35], 0, v[128:129]
	s_mov_b32 m0, s36
	s_nop 0
	global_load_lds_dwordx4 v[168:169], off sc1
	v_lshl_add_u64 v[168:169], s[34:35], 0, v[130:131]
	s_add_i32 m0, s36, 0x2000
	s_nop 0
	global_load_lds_dwordx4 v[168:169], off sc1
	v_lshl_add_u64 v[168:169], v[220:221], 0, s[18:19]
	s_mov_b32 m0, s49
	s_nop 0
	global_load_lds_dwordx4 v[168:169], off sc1
	v_lshl_add_u64 v[168:169], v[222:223], 0, s[18:19]
	s_mov_b32 m0, s50
	s_nop 0
	global_load_lds_dwordx4 v[168:169], off sc1
	s_waitcnt vmcnt(8)
	s_waitcnt lgkmcnt(0)
	s_barrier
	s_setprio 1
	s_waitcnt lgkmcnt(0)
	v_mfma_f32_16x16x32_bf16 v[60:63], v[148:151], v[184:187], v[60:63]
	v_mfma_f32_16x16x32_bf16 v[56:59], v[156:159], v[184:187], v[56:59]
	v_mfma_f32_16x16x32_bf16 v[44:47], v[148:151], v[192:195], v[44:47]
	v_mfma_f32_16x16x32_bf16 v[40:43], v[156:159], v[192:195], v[40:43]
	v_mfma_f32_16x16x32_bf16 v[28:31], v[148:151], v[202:205], v[28:31]
	v_mfma_f32_16x16x32_bf16 v[24:27], v[156:159], v[202:205], v[24:27]
	v_mfma_f32_16x16x32_bf16 v[12:15], v[148:151], v[210:213], v[12:15]
	v_mfma_f32_16x16x32_bf16 v[8:11], v[156:159], v[210:213], v[8:11]
	v_mfma_f32_16x16x32_bf16 v[60:63], v[152:155], v[188:191], v[60:63]
	v_mfma_f32_16x16x32_bf16 v[56:59], v[160:163], v[188:191], v[56:59]
	v_mfma_f32_16x16x32_bf16 v[44:47], v[152:155], v[196:199], v[44:47]
	v_mfma_f32_16x16x32_bf16 v[40:43], v[160:163], v[196:199], v[40:43]
	v_mfma_f32_16x16x32_bf16 v[28:31], v[152:155], v[206:209], v[28:31]
	v_mfma_f32_16x16x32_bf16 v[24:27], v[160:163], v[206:209], v[24:27]
	v_mfma_f32_16x16x32_bf16 v[12:15], v[152:155], v[214:217], v[12:15]
	v_mfma_f32_16x16x32_bf16 v[8:11], v[160:163], v[214:217], v[8:11]
	s_setprio 0
	s_setprio 1
	v_mfma_f32_16x16x32_bf16 v[52:55], v[164:167], v[184:187], v[52:55]
	v_mfma_f32_16x16x32_bf16 v[48:51], v[176:179], v[184:187], v[48:51]
	v_mfma_f32_16x16x32_bf16 v[36:39], v[164:167], v[192:195], v[36:39]
	v_mfma_f32_16x16x32_bf16 v[32:35], v[176:179], v[192:195], v[32:35]
	v_mfma_f32_16x16x32_bf16 v[20:23], v[164:167], v[202:205], v[20:23]
	v_mfma_f32_16x16x32_bf16 v[16:19], v[176:179], v[202:205], v[16:19]
	v_mfma_f32_16x16x32_bf16 v[4:7], v[164:167], v[210:213], v[4:7]
	v_mfma_f32_16x16x32_bf16 v[0:3], v[176:179], v[210:213], v[0:3]
	v_mfma_f32_16x16x32_bf16 v[52:55], v[172:175], v[188:191], v[52:55]
	v_mfma_f32_16x16x32_bf16 v[48:51], v[180:183], v[188:191], v[48:51]
	v_mfma_f32_16x16x32_bf16 v[36:39], v[172:175], v[196:199], v[36:39]
	v_mfma_f32_16x16x32_bf16 v[32:35], v[180:183], v[196:199], v[32:35]
	v_mfma_f32_16x16x32_bf16 v[20:23], v[172:175], v[206:209], v[20:23]
	v_mfma_f32_16x16x32_bf16 v[16:19], v[180:183], v[206:209], v[16:19]
	v_mfma_f32_16x16x32_bf16 v[4:7], v[172:175], v[214:217], v[4:7]
	v_mfma_f32_16x16x32_bf16 v[0:3], v[180:183], v[214:217], v[0:3]
	s_setprio 0
	s_barrier
	s_add_i32 s58, s58, 2
	s_add_u32 s30, s30, 0x100
	s_addc_u32 s31, s31, 0
	s_cmp_gt_u32 s58, 29
	s_cbranch_scc0 .LBB0_495
	s_add_u32 s30, s27, 0xffffff00
	s_addc_u32 s31, s55, -1
	s_andn2_b64 vcc, exec, s[4:5]
	s_cbranch_vccnz .LBB0_498
	v_mov_b32_e32 v0, 0
	s_mov_b32 s51, s20
	s_mov_b32 s14, s22
	s_mov_b64 s[16:17], s[28:29]
	s_mov_b32 s52, s26
	v_mov_b32_e32 v1, v0
	v_mov_b32_e32 v2, v0
	v_mov_b32_e32 v3, v0
	v_mov_b32_e32 v4, v0
	v_mov_b32_e32 v5, v0
	v_mov_b32_e32 v6, v0
	v_mov_b32_e32 v7, v0
	v_mov_b32_e32 v16, v0
	v_mov_b32_e32 v17, v0
	v_mov_b32_e32 v18, v0
	v_mov_b32_e32 v19, v0
	v_mov_b32_e32 v20, v0
	v_mov_b32_e32 v21, v0
	v_mov_b32_e32 v22, v0
	v_mov_b32_e32 v23, v0
	v_mov_b32_e32 v32, v0
	v_mov_b32_e32 v33, v0
	v_mov_b32_e32 v34, v0
	v_mov_b32_e32 v35, v0
	v_mov_b32_e32 v36, v0
	v_mov_b32_e32 v37, v0
	v_mov_b32_e32 v38, v0
	v_mov_b32_e32 v39, v0
	v_mov_b32_e32 v48, v0
	v_mov_b32_e32 v49, v0
	v_mov_b32_e32 v50, v0
	v_mov_b32_e32 v51, v0
	v_mov_b32_e32 v52, v0
	v_mov_b32_e32 v53, v0
	v_mov_b32_e32 v54, v0
	v_mov_b32_e32 v55, v0
	v_mov_b32_e32 v8, v0
	v_mov_b32_e32 v9, v0
	v_mov_b32_e32 v10, v0
	v_mov_b32_e32 v11, v0
	v_mov_b32_e32 v12, v0
	v_mov_b32_e32 v13, v0
	v_mov_b32_e32 v14, v0
	v_mov_b32_e32 v15, v0
	v_mov_b32_e32 v24, v0
	v_mov_b32_e32 v25, v0
	v_mov_b32_e32 v26, v0
	v_mov_b32_e32 v27, v0
	v_mov_b32_e32 v28, v0
	v_mov_b32_e32 v29, v0
	v_mov_b32_e32 v30, v0
	v_mov_b32_e32 v31, v0
	v_mov_b32_e32 v40, v0
	v_mov_b32_e32 v41, v0
	v_mov_b32_e32 v42, v0
	v_mov_b32_e32 v43, v0
	v_mov_b32_e32 v44, v0
	v_mov_b32_e32 v45, v0
	v_mov_b32_e32 v46, v0
	v_mov_b32_e32 v47, v0
	v_mov_b32_e32 v56, v0
	v_mov_b32_e32 v57, v0
	v_mov_b32_e32 v58, v0
	v_mov_b32_e32 v59, v0
	v_mov_b32_e32 v60, v0
	v_mov_b32_e32 v61, v0
	v_mov_b32_e32 v62, v0
	v_mov_b32_e32 v63, v0
	v_mov_b32_e32 v64, v0
	v_mov_b32_e32 v65, v0
	v_mov_b32_e32 v66, v0
	v_mov_b32_e32 v67, v0
	v_mov_b32_e32 v68, v0
	v_mov_b32_e32 v69, v0
	v_mov_b32_e32 v70, v0
	v_mov_b32_e32 v71, v0
	v_mov_b32_e32 v80, v0
	v_mov_b32_e32 v81, v0
	v_mov_b32_e32 v82, v0
	v_mov_b32_e32 v83, v0
	v_mov_b32_e32 v84, v0
	v_mov_b32_e32 v85, v0
	v_mov_b32_e32 v86, v0
	v_mov_b32_e32 v87, v0
	v_mov_b32_e32 v96, v0
	v_mov_b32_e32 v97, v0
	v_mov_b32_e32 v98, v0
	v_mov_b32_e32 v99, v0
	v_mov_b32_e32 v100, v0
	v_mov_b32_e32 v101, v0
	v_mov_b32_e32 v102, v0
	v_mov_b32_e32 v103, v0
	v_mov_b32_e32 v112, v0
	v_mov_b32_e32 v113, v0
	v_mov_b32_e32 v114, v0
	v_mov_b32_e32 v115, v0
	v_mov_b32_e32 v116, v0
	v_mov_b32_e32 v117, v0
	v_mov_b32_e32 v118, v0
	v_mov_b32_e32 v119, v0
	v_mov_b32_e32 v72, v0
	v_mov_b32_e32 v73, v0
	v_mov_b32_e32 v74, v0
	v_mov_b32_e32 v75, v0
	v_mov_b32_e32 v76, v0
	v_mov_b32_e32 v77, v0
	v_mov_b32_e32 v78, v0
	v_mov_b32_e32 v79, v0
	v_mov_b32_e32 v88, v0
	v_mov_b32_e32 v89, v0
	v_mov_b32_e32 v90, v0
	v_mov_b32_e32 v91, v0
	v_mov_b32_e32 v92, v0
	v_mov_b32_e32 v93, v0
	v_mov_b32_e32 v94, v0
	v_mov_b32_e32 v95, v0
	v_mov_b32_e32 v104, v0
	v_mov_b32_e32 v105, v0
	v_mov_b32_e32 v106, v0
	v_mov_b32_e32 v107, v0
	v_mov_b32_e32 v108, v0
	v_mov_b32_e32 v109, v0
	v_mov_b32_e32 v110, v0
	v_mov_b32_e32 v111, v0
	v_mov_b32_e32 v120, v0
	v_mov_b32_e32 v121, v0
	v_mov_b32_e32 v122, v0
	v_mov_b32_e32 v123, v0
	v_mov_b32_e32 v124, v0
	v_mov_b32_e32 v125, v0
	v_mov_b32_e32 v126, v0
	v_mov_b32_e32 v127, v0
	s_andn2_b64 vcc, exec, s[0:1]
	s_cbranch_vccnz .LBB0_499
	s_branch .LBB0_500
